# c13 + split-K reducer reloads partials as one continuous 23-deep software pipeline instead of six drained batches of 16
# speedup vs baseline: 1.0057x; 1.0033x over previous
.Lsk8_polled:
	s_or_b64 exec, exec, s[80:81]
	s_barrier
	global_load_dwordx4 v[152:155], v150, s[84:85] sc1
	s_add_u32 s84, s84, s62
	s_addc_u32 s85, s85, 0
	global_load_dwordx4 v[156:159], v150, s[84:85] sc1
	s_add_u32 s84, s84, s62
	s_addc_u32 s85, s85, 0
	global_load_dwordx4 v[160:163], v150, s[84:85] sc1
	s_add_u32 s84, s84, s62
	s_addc_u32 s85, s85, 0
	global_load_dwordx4 v[164:167], v150, s[84:85] sc1
	s_add_u32 s84, s84, s62
	s_addc_u32 s85, s85, 0
	global_load_dwordx4 v[168:171], v150, s[84:85] sc1
	s_add_u32 s84, s84, s62
	s_addc_u32 s85, s85, 0
	global_load_dwordx4 v[172:175], v150, s[84:85] sc1
	s_add_u32 s84, s84, s62
	s_addc_u32 s85, s85, 0
	global_load_dwordx4 v[176:179], v150, s[84:85] sc1
	s_add_u32 s84, s84, s62
	s_addc_u32 s85, s85, 0
	global_load_dwordx4 v[180:183], v150, s[84:85] sc1
	s_add_u32 s84, s84, s62
	s_addc_u32 s85, s85, 0
	global_load_dwordx4 v[184:187], v150, s[84:85] sc1
	s_add_u32 s84, s84, s62
	s_addc_u32 s85, s85, 0
	global_load_dwordx4 v[192:195], v150, s[84:85] sc1
	s_add_u32 s84, s84, s62
	s_addc_u32 s85, s85, 0
	global_load_dwordx4 v[196:199], v150, s[84:85] sc1
	s_add_u32 s84, s84, s62
	s_addc_u32 s85, s85, 0
	global_load_dwordx4 v[200:203], v150, s[84:85] sc1
	s_add_u32 s84, s84, s62
	s_addc_u32 s85, s85, 0
	global_load_dwordx4 v[204:207], v150, s[84:85] sc1
	s_add_u32 s84, s84, s62
	s_addc_u32 s85, s85, 0
	global_load_dwordx4 v[208:211], v150, s[84:85] sc1
	s_add_u32 s84, s84, s62
	s_addc_u32 s85, s85, 0
	global_load_dwordx4 v[212:215], v150, s[84:85] sc1
	s_add_u32 s84, s84, s62
	s_addc_u32 s85, s85, 0
	global_load_dwordx4 v[216:219], v150, s[84:85] sc1
	s_add_u32 s84, s84, s62
	s_addc_u32 s85, s85, 0
	global_load_dwordx4 v[228:231], v150, s[84:85] sc1
	s_add_u32 s84, s84, s62
	s_addc_u32 s85, s85, 0
	global_load_dwordx4 v[232:235], v150, s[84:85] sc1
	s_add_u32 s84, s84, s62
	s_addc_u32 s85, s85, 0
	global_load_dwordx4 v[236:239], v150, s[84:85] sc1
	s_add_u32 s84, s84, s62
	s_addc_u32 s85, s85, 0
	global_load_dwordx4 v[240:243], v150, s[84:85] sc1
	s_add_u32 s84, s84, s62
	s_addc_u32 s85, s85, 0
	global_load_dwordx4 v[244:247], v150, s[84:85] sc1
	s_add_u32 s84, s84, s62
	s_addc_u32 s85, s85, 0
	global_load_dwordx4 v[248:251], v150, s[84:85] sc1
	s_add_u32 s84, s84, s62
	s_addc_u32 s85, s85, 0
	global_load_dwordx4 v[252:255], v150, s[84:85] sc1
	s_add_u32 s84, s84, s62
	s_addc_u32 s85, s85, 0
	s_waitcnt vmcnt(22)
	v_pk_add_f32 v[0:1], v[0:1], v[152:153]
	v_pk_add_f32 v[2:3], v[2:3], v[154:155]
	global_load_dwordx4 v[152:155], v150, s[84:85] sc1
	s_add_u32 s84, s84, s62
	s_addc_u32 s85, s85, 0
	s_waitcnt vmcnt(22)
	v_pk_add_f32 v[4:5], v[4:5], v[156:157]
	v_pk_add_f32 v[6:7], v[6:7], v[158:159]
	global_load_dwordx4 v[156:159], v150, s[84:85] sc1
	s_add_u32 s84, s84, s62
	s_addc_u32 s85, s85, 0
	s_waitcnt vmcnt(22)
	v_pk_add_f32 v[8:9], v[8:9], v[160:161]
	v_pk_add_f32 v[10:11], v[10:11], v[162:163]
	global_load_dwordx4 v[160:163], v150, s[84:85] sc1
	s_add_u32 s84, s84, s62
	s_addc_u32 s85, s85, 0
	s_waitcnt vmcnt(22)
	v_pk_add_f32 v[12:13], v[12:13], v[164:165]
	v_pk_add_f32 v[14:15], v[14:15], v[166:167]
	global_load_dwordx4 v[164:167], v150, s[84:85] sc1
	s_add_u32 s84, s84, s62
	s_addc_u32 s85, s85, 0
	s_waitcnt vmcnt(22)
	v_pk_add_f32 v[16:17], v[16:17], v[168:169]
	v_pk_add_f32 v[18:19], v[18:19], v[170:171]
	global_load_dwordx4 v[168:171], v150, s[84:85] sc1
	s_add_u32 s84, s84, s62
	s_addc_u32 s85, s85, 0
	s_waitcnt vmcnt(22)
	v_pk_add_f32 v[20:21], v[20:21], v[172:173]
	v_pk_add_f32 v[22:23], v[22:23], v[174:175]
	global_load_dwordx4 v[172:175], v150, s[84:85] sc1
	s_add_u32 s84, s84, s62
	s_addc_u32 s85, s85, 0
	s_waitcnt vmcnt(22)
	v_pk_add_f32 v[24:25], v[24:25], v[176:177]
	v_pk_add_f32 v[26:27], v[26:27], v[178:179]
	global_load_dwordx4 v[176:179], v150, s[84:85] sc1
	s_add_u32 s84, s84, s62
	s_addc_u32 s85, s85, 0
	s_waitcnt vmcnt(22)
	v_pk_add_f32 v[28:29], v[28:29], v[180:181]
	v_pk_add_f32 v[30:31], v[30:31], v[182:183]
	global_load_dwordx4 v[180:183], v150, s[84:85] sc1
	s_add_u32 s84, s84, s62
	s_addc_u32 s85, s85, 0
	s_waitcnt vmcnt(22)
	v_pk_add_f32 v[32:33], v[32:33], v[184:185]
	v_pk_add_f32 v[34:35], v[34:35], v[186:187]
	global_load_dwordx4 v[184:187], v150, s[84:85] sc1
	s_add_u32 s84, s84, s62
	s_addc_u32 s85, s85, 0
	s_waitcnt vmcnt(22)
	v_pk_add_f32 v[36:37], v[36:37], v[192:193]
	v_pk_add_f32 v[38:39], v[38:39], v[194:195]
	global_load_dwordx4 v[192:195], v150, s[84:85] sc1
	s_add_u32 s84, s84, s62
	s_addc_u32 s85, s85, 0
	s_waitcnt vmcnt(22)
	v_pk_add_f32 v[40:41], v[40:41], v[196:197]
	v_pk_add_f32 v[42:43], v[42:43], v[198:199]
	global_load_dwordx4 v[196:199], v150, s[84:85] sc1
	s_add_u32 s84, s84, s62
	s_addc_u32 s85, s85, 0
	s_waitcnt vmcnt(22)
	v_pk_add_f32 v[44:45], v[44:45], v[200:201]
	v_pk_add_f32 v[46:47], v[46:47], v[202:203]
	global_load_dwordx4 v[200:203], v150, s[84:85] sc1
	s_add_u32 s84, s84, s62
	s_addc_u32 s85, s85, 0
	s_waitcnt vmcnt(22)
	v_pk_add_f32 v[48:49], v[48:49], v[204:205]
	v_pk_add_f32 v[50:51], v[50:51], v[206:207]
	global_load_dwordx4 v[204:207], v150, s[84:85] sc1
	s_add_u32 s84, s84, s62
	s_addc_u32 s85, s85, 0
	s_waitcnt vmcnt(22)
	v_pk_add_f32 v[52:53], v[52:53], v[208:209]
	v_pk_add_f32 v[54:55], v[54:55], v[210:211]
	global_load_dwordx4 v[208:211], v150, s[84:85] sc1
	s_add_u32 s84, s84, s62
	s_addc_u32 s85, s85, 0
	s_waitcnt vmcnt(22)
	v_pk_add_f32 v[56:57], v[56:57], v[212:213]
	v_pk_add_f32 v[58:59], v[58:59], v[214:215]
	global_load_dwordx4 v[212:215], v150, s[84:85] sc1
	s_add_u32 s84, s84, s62
	s_addc_u32 s85, s85, 0
	s_waitcnt vmcnt(22)
	v_pk_add_f32 v[60:61], v[60:61], v[216:217]
	v_pk_add_f32 v[62:63], v[62:63], v[218:219]
	global_load_dwordx4 v[216:219], v150, s[84:85] sc1
	s_add_u32 s84, s84, s62
	s_addc_u32 s85, s85, 0
	s_waitcnt vmcnt(22)
	v_pk_add_f32 v[64:65], v[64:65], v[228:229]
	v_pk_add_f32 v[66:67], v[66:67], v[230:231]
	global_load_dwordx4 v[228:231], v150, s[84:85] sc1
	s_add_u32 s84, s84, s62
	s_addc_u32 s85, s85, 0
	s_waitcnt vmcnt(22)
	v_pk_add_f32 v[68:69], v[68:69], v[232:233]
	v_pk_add_f32 v[70:71], v[70:71], v[234:235]
	global_load_dwordx4 v[232:235], v150, s[84:85] sc1
	s_add_u32 s84, s84, s62
	s_addc_u32 s85, s85, 0
	s_waitcnt vmcnt(22)
	v_pk_add_f32 v[72:73], v[72:73], v[236:237]
	v_pk_add_f32 v[74:75], v[74:75], v[238:239]
	global_load_dwordx4 v[236:239], v150, s[84:85] sc1
	s_add_u32 s84, s84, s62
	s_addc_u32 s85, s85, 0
	s_waitcnt vmcnt(22)
	v_pk_add_f32 v[76:77], v[76:77], v[240:241]
	v_pk_add_f32 v[78:79], v[78:79], v[242:243]
	global_load_dwordx4 v[240:243], v150, s[84:85] sc1
	s_add_u32 s84, s84, s62
	s_addc_u32 s85, s85, 0
	s_waitcnt vmcnt(22)
	v_pk_add_f32 v[80:81], v[80:81], v[244:245]
	v_pk_add_f32 v[82:83], v[82:83], v[246:247]
	global_load_dwordx4 v[244:247], v150, s[84:85] sc1
	s_add_u32 s84, s84, s62
	s_addc_u32 s85, s85, 0
	s_waitcnt vmcnt(22)
	v_pk_add_f32 v[84:85], v[84:85], v[248:249]
	v_pk_add_f32 v[86:87], v[86:87], v[250:251]
	global_load_dwordx4 v[248:251], v150, s[84:85] sc1
	s_add_u32 s84, s84, s62
	s_addc_u32 s85, s85, 0
	s_waitcnt vmcnt(22)
	v_pk_add_f32 v[88:89], v[88:89], v[252:253]
	v_pk_add_f32 v[90:91], v[90:91], v[254:255]
	global_load_dwordx4 v[252:255], v150, s[84:85] sc1
	s_add_u32 s84, s84, s62
	s_addc_u32 s85, s85, 0
	s_waitcnt vmcnt(22)
	v_pk_add_f32 v[92:93], v[92:93], v[152:153]
	v_pk_add_f32 v[94:95], v[94:95], v[154:155]
	global_load_dwordx4 v[152:155], v150, s[84:85] sc1
	s_add_u32 s84, s84, s62
	s_addc_u32 s85, s85, 0
	s_waitcnt vmcnt(22)
	v_pk_add_f32 v[96:97], v[96:97], v[156:157]
	v_pk_add_f32 v[98:99], v[98:99], v[158:159]
	global_load_dwordx4 v[156:159], v150, s[84:85] sc1
	s_add_u32 s84, s84, s62
	s_addc_u32 s85, s85, 0
	s_waitcnt vmcnt(22)
	v_pk_add_f32 v[100:101], v[100:101], v[160:161]
	v_pk_add_f32 v[102:103], v[102:103], v[162:163]
	global_load_dwordx4 v[160:163], v150, s[84:85] sc1
	s_add_u32 s84, s84, s62
	s_addc_u32 s85, s85, 0
	s_waitcnt vmcnt(22)
	v_pk_add_f32 v[104:105], v[104:105], v[164:165]
	v_pk_add_f32 v[106:107], v[106:107], v[166:167]
	global_load_dwordx4 v[164:167], v150, s[84:85] sc1
	s_add_u32 s84, s84, s62
	s_addc_u32 s85, s85, 0
	s_waitcnt vmcnt(22)
	v_pk_add_f32 v[108:109], v[108:109], v[168:169]
	v_pk_add_f32 v[110:111], v[110:111], v[170:171]
	global_load_dwordx4 v[168:171], v150, s[84:85] sc1
	s_add_u32 s84, s84, s62
	s_addc_u32 s85, s85, 0
	s_waitcnt vmcnt(22)
	v_pk_add_f32 v[112:113], v[112:113], v[172:173]
	v_pk_add_f32 v[114:115], v[114:115], v[174:175]
	global_load_dwordx4 v[172:175], v150, s[84:85] sc1
	s_add_u32 s84, s84, s62
	s_addc_u32 s85, s85, 0
	s_waitcnt vmcnt(22)
	v_pk_add_f32 v[116:117], v[116:117], v[176:177]
	v_pk_add_f32 v[118:119], v[118:119], v[178:179]
	global_load_dwordx4 v[176:179], v150, s[84:85] sc1
	s_add_u32 s84, s84, s62
	s_addc_u32 s85, s85, 0
	s_waitcnt vmcnt(22)
	v_pk_add_f32 v[120:121], v[120:121], v[180:181]
	v_pk_add_f32 v[122:123], v[122:123], v[182:183]
	global_load_dwordx4 v[180:183], v150, s[84:85] sc1
	s_add_u32 s84, s84, s62
	s_addc_u32 s85, s85, 0
	s_waitcnt vmcnt(22)
	v_pk_add_f32 v[124:125], v[124:125], v[184:185]
	v_pk_add_f32 v[126:127], v[126:127], v[186:187]
	global_load_dwordx4 v[184:187], v150, s[84:85] sc1
	s_add_u32 s84, s84, s62
	s_addc_u32 s85, s85, 0
	s_waitcnt vmcnt(22)
	v_pk_add_f32 v[0:1], v[0:1], v[192:193]
	v_pk_add_f32 v[2:3], v[2:3], v[194:195]
	global_load_dwordx4 v[192:195], v150, s[84:85] sc1
	s_add_u32 s84, s84, s62
	s_addc_u32 s85, s85, 0
	s_waitcnt vmcnt(22)
	v_pk_add_f32 v[4:5], v[4:5], v[196:197]
	v_pk_add_f32 v[6:7], v[6:7], v[198:199]
	global_load_dwordx4 v[196:199], v150, s[84:85] sc1
	s_add_u32 s84, s84, s62
	s_addc_u32 s85, s85, 0
	s_waitcnt vmcnt(22)
	v_pk_add_f32 v[8:9], v[8:9], v[200:201]
	v_pk_add_f32 v[10:11], v[10:11], v[202:203]
	global_load_dwordx4 v[200:203], v150, s[84:85] sc1
	s_add_u32 s84, s84, s62
	s_addc_u32 s85, s85, 0
	s_waitcnt vmcnt(22)
	v_pk_add_f32 v[12:13], v[12:13], v[204:205]
	v_pk_add_f32 v[14:15], v[14:15], v[206:207]
	global_load_dwordx4 v[204:207], v150, s[84:85] sc1
	s_add_u32 s84, s84, s62
	s_addc_u32 s85, s85, 0
	s_waitcnt vmcnt(22)
	v_pk_add_f32 v[16:17], v[16:17], v[208:209]
	v_pk_add_f32 v[18:19], v[18:19], v[210:211]
	global_load_dwordx4 v[208:211], v150, s[84:85] sc1
	s_add_u32 s84, s84, s62
	s_addc_u32 s85, s85, 0
	s_waitcnt vmcnt(22)
	v_pk_add_f32 v[20:21], v[20:21], v[212:213]
	v_pk_add_f32 v[22:23], v[22:23], v[214:215]
	global_load_dwordx4 v[212:215], v150, s[84:85] sc1
	s_add_u32 s84, s84, s62
	s_addc_u32 s85, s85, 0
	s_waitcnt vmcnt(22)
	v_pk_add_f32 v[24:25], v[24:25], v[216:217]
	v_pk_add_f32 v[26:27], v[26:27], v[218:219]
	global_load_dwordx4 v[216:219], v150, s[84:85] sc1
	s_add_u32 s84, s84, s62
	s_addc_u32 s85, s85, 0
	s_waitcnt vmcnt(22)
	v_pk_add_f32 v[28:29], v[28:29], v[228:229]
	v_pk_add_f32 v[30:31], v[30:31], v[230:231]
	global_load_dwordx4 v[228:231], v150, s[84:85] sc1
	s_add_u32 s84, s84, s62
	s_addc_u32 s85, s85, 0
	s_waitcnt vmcnt(22)
	v_pk_add_f32 v[32:33], v[32:33], v[232:233]
	v_pk_add_f32 v[34:35], v[34:35], v[234:235]
	global_load_dwordx4 v[232:235], v150, s[84:85] sc1
	s_add_u32 s84, s84, s62
	s_addc_u32 s85, s85, 0
	s_waitcnt vmcnt(22)
	v_pk_add_f32 v[36:37], v[36:37], v[236:237]
	v_pk_add_f32 v[38:39], v[38:39], v[238:239]
	global_load_dwordx4 v[236:239], v150, s[84:85] sc1
	s_add_u32 s84, s84, s62
	s_addc_u32 s85, s85, 0
	s_waitcnt vmcnt(22)
	v_pk_add_f32 v[40:41], v[40:41], v[240:241]
	v_pk_add_f32 v[42:43], v[42:43], v[242:243]
	global_load_dwordx4 v[240:243], v150, s[84:85] sc1
	s_add_u32 s84, s84, s62
	s_addc_u32 s85, s85, 0
	s_waitcnt vmcnt(22)
	v_pk_add_f32 v[44:45], v[44:45], v[244:245]
	v_pk_add_f32 v[46:47], v[46:47], v[246:247]
	global_load_dwordx4 v[244:247], v150, s[84:85] sc1
	s_add_u32 s84, s84, s62
	s_addc_u32 s85, s85, 0
	s_waitcnt vmcnt(22)
	v_pk_add_f32 v[48:49], v[48:49], v[248:249]
	v_pk_add_f32 v[50:51], v[50:51], v[250:251]
	global_load_dwordx4 v[248:251], v150, s[84:85] sc1
	s_add_u32 s84, s84, s62
	s_addc_u32 s85, s85, 0
	s_waitcnt vmcnt(22)
	v_pk_add_f32 v[52:53], v[52:53], v[252:253]
	v_pk_add_f32 v[54:55], v[54:55], v[254:255]
	global_load_dwordx4 v[252:255], v150, s[84:85] sc1
	s_add_u32 s84, s84, s62
	s_addc_u32 s85, s85, 0
	s_waitcnt vmcnt(22)
	v_pk_add_f32 v[56:57], v[56:57], v[152:153]
	v_pk_add_f32 v[58:59], v[58:59], v[154:155]
	global_load_dwordx4 v[152:155], v150, s[84:85] sc1
	s_add_u32 s84, s84, s62
	s_addc_u32 s85, s85, 0
	s_waitcnt vmcnt(22)
	v_pk_add_f32 v[60:61], v[60:61], v[156:157]
	v_pk_add_f32 v[62:63], v[62:63], v[158:159]
	global_load_dwordx4 v[156:159], v150, s[84:85] sc1
	s_add_u32 s84, s84, s62
	s_addc_u32 s85, s85, 0
	s_waitcnt vmcnt(22)
	v_pk_add_f32 v[64:65], v[64:65], v[160:161]
	v_pk_add_f32 v[66:67], v[66:67], v[162:163]
	global_load_dwordx4 v[160:163], v150, s[84:85] sc1
	s_add_u32 s84, s84, s62
	s_addc_u32 s85, s85, 0
	s_waitcnt vmcnt(22)
	v_pk_add_f32 v[68:69], v[68:69], v[164:165]
	v_pk_add_f32 v[70:71], v[70:71], v[166:167]
	global_load_dwordx4 v[164:167], v150, s[84:85] sc1
	s_add_u32 s84, s84, s62
	s_addc_u32 s85, s85, 0
	s_waitcnt vmcnt(22)
	v_pk_add_f32 v[72:73], v[72:73], v[168:169]
	v_pk_add_f32 v[74:75], v[74:75], v[170:171]
	global_load_dwordx4 v[168:171], v150, s[84:85] sc1
	s_add_u32 s84, s84, s62
	s_addc_u32 s85, s85, 0
	s_waitcnt vmcnt(22)
	v_pk_add_f32 v[76:77], v[76:77], v[172:173]
	v_pk_add_f32 v[78:79], v[78:79], v[174:175]
	global_load_dwordx4 v[172:175], v150, s[84:85] sc1
	s_add_u32 s84, s84, s62
	s_addc_u32 s85, s85, 0
	s_waitcnt vmcnt(22)
	v_pk_add_f32 v[80:81], v[80:81], v[176:177]
	v_pk_add_f32 v[82:83], v[82:83], v[178:179]
	global_load_dwordx4 v[176:179], v150, s[84:85] sc1
	s_add_u32 s84, s84, s62
	s_addc_u32 s85, s85, 0
	s_waitcnt vmcnt(22)
	v_pk_add_f32 v[84:85], v[84:85], v[180:181]
	v_pk_add_f32 v[86:87], v[86:87], v[182:183]
	global_load_dwordx4 v[180:183], v150, s[84:85] sc1
	s_add_u32 s84, s84, s62
	s_addc_u32 s85, s85, 0
	s_waitcnt vmcnt(22)
	v_pk_add_f32 v[88:89], v[88:89], v[184:185]
	v_pk_add_f32 v[90:91], v[90:91], v[186:187]
	global_load_dwordx4 v[184:187], v150, s[84:85] sc1
	s_add_u32 s84, s84, s62
	s_addc_u32 s85, s85, 0
	s_waitcnt vmcnt(22)
	v_pk_add_f32 v[92:93], v[92:93], v[192:193]
	v_pk_add_f32 v[94:95], v[94:95], v[194:195]
	global_load_dwordx4 v[192:195], v150, s[84:85] sc1
	s_add_u32 s84, s84, s62
	s_addc_u32 s85, s85, 0
	s_waitcnt vmcnt(22)
	v_pk_add_f32 v[96:97], v[96:97], v[196:197]
	v_pk_add_f32 v[98:99], v[98:99], v[198:199]
	global_load_dwordx4 v[196:199], v150, s[84:85] sc1
	s_add_u32 s84, s84, s62
	s_addc_u32 s85, s85, 0
	s_waitcnt vmcnt(22)
	v_pk_add_f32 v[100:101], v[100:101], v[200:201]
	v_pk_add_f32 v[102:103], v[102:103], v[202:203]
	global_load_dwordx4 v[200:203], v150, s[84:85] sc1
	s_add_u32 s84, s84, s62
	s_addc_u32 s85, s85, 0
	s_waitcnt vmcnt(22)
	v_pk_add_f32 v[104:105], v[104:105], v[204:205]
	v_pk_add_f32 v[106:107], v[106:107], v[206:207]
	global_load_dwordx4 v[204:207], v150, s[84:85] sc1
	s_add_u32 s84, s84, s62
	s_addc_u32 s85, s85, 0
	s_waitcnt vmcnt(22)
	v_pk_add_f32 v[108:109], v[108:109], v[208:209]
	v_pk_add_f32 v[110:111], v[110:111], v[210:211]
	global_load_dwordx4 v[208:211], v150, s[84:85] sc1
	s_add_u32 s84, s84, s62
	s_addc_u32 s85, s85, 0
	s_waitcnt vmcnt(22)
	v_pk_add_f32 v[112:113], v[112:113], v[212:213]
	v_pk_add_f32 v[114:115], v[114:115], v[214:215]
	global_load_dwordx4 v[212:215], v150, s[84:85] sc1
	s_add_u32 s84, s84, s62
	s_addc_u32 s85, s85, 0
	s_waitcnt vmcnt(22)
	v_pk_add_f32 v[116:117], v[116:117], v[216:217]
	v_pk_add_f32 v[118:119], v[118:119], v[218:219]
	global_load_dwordx4 v[216:219], v150, s[84:85] sc1
	s_add_u32 s84, s84, s62
	s_addc_u32 s85, s85, 0
	s_waitcnt vmcnt(22)
	v_pk_add_f32 v[120:121], v[120:121], v[228:229]
	v_pk_add_f32 v[122:123], v[122:123], v[230:231]
	global_load_dwordx4 v[228:231], v150, s[84:85] sc1
	s_add_u32 s84, s84, s62
	s_addc_u32 s85, s85, 0
	s_waitcnt vmcnt(22)
	v_pk_add_f32 v[124:125], v[124:125], v[232:233]
	v_pk_add_f32 v[126:127], v[126:127], v[234:235]
	global_load_dwordx4 v[232:235], v150, s[84:85] sc1
	s_add_u32 s84, s84, s62
	s_addc_u32 s85, s85, 0
	s_waitcnt vmcnt(22)
	v_pk_add_f32 v[0:1], v[0:1], v[236:237]
	v_pk_add_f32 v[2:3], v[2:3], v[238:239]
	global_load_dwordx4 v[236:239], v150, s[84:85] sc1
	s_add_u32 s84, s84, s62
	s_addc_u32 s85, s85, 0
	s_waitcnt vmcnt(22)
	v_pk_add_f32 v[4:5], v[4:5], v[240:241]
	v_pk_add_f32 v[6:7], v[6:7], v[242:243]
	global_load_dwordx4 v[240:243], v150, s[84:85] sc1
	s_add_u32 s84, s84, s62
	s_addc_u32 s85, s85, 0
	s_waitcnt vmcnt(22)
	v_pk_add_f32 v[8:9], v[8:9], v[244:245]
	v_pk_add_f32 v[10:11], v[10:11], v[246:247]
	global_load_dwordx4 v[244:247], v150, s[84:85] sc1
	s_add_u32 s84, s84, s62
	s_addc_u32 s85, s85, 0
	s_waitcnt vmcnt(22)
	v_pk_add_f32 v[12:13], v[12:13], v[248:249]
	v_pk_add_f32 v[14:15], v[14:15], v[250:251]
	global_load_dwordx4 v[248:251], v150, s[84:85] sc1
	s_add_u32 s84, s84, s62
	s_addc_u32 s85, s85, 0
	s_waitcnt vmcnt(22)
	v_pk_add_f32 v[16:17], v[16:17], v[252:253]
	v_pk_add_f32 v[18:19], v[18:19], v[254:255]
	global_load_dwordx4 v[252:255], v150, s[84:85] sc1
	s_add_u32 s84, s84, s62
	s_addc_u32 s85, s85, 0
	s_waitcnt vmcnt(22)
	v_pk_add_f32 v[20:21], v[20:21], v[152:153]
	v_pk_add_f32 v[22:23], v[22:23], v[154:155]
	global_load_dwordx4 v[152:155], v150, s[84:85] sc1
	s_add_u32 s84, s84, s62
	s_addc_u32 s85, s85, 0
	s_waitcnt vmcnt(22)
	v_pk_add_f32 v[24:25], v[24:25], v[156:157]
	v_pk_add_f32 v[26:27], v[26:27], v[158:159]
	global_load_dwordx4 v[156:159], v150, s[84:85] sc1
	s_add_u32 s84, s84, s62
	s_addc_u32 s85, s85, 0
	s_waitcnt vmcnt(22)
	v_pk_add_f32 v[28:29], v[28:29], v[160:161]
	v_pk_add_f32 v[30:31], v[30:31], v[162:163]
	global_load_dwordx4 v[160:163], v150, s[84:85] sc1
	s_add_u32 s84, s84, s62
	s_addc_u32 s85, s85, 0
	s_waitcnt vmcnt(22)
	v_pk_add_f32 v[32:33], v[32:33], v[164:165]
	v_pk_add_f32 v[34:35], v[34:35], v[166:167]
	global_load_dwordx4 v[164:167], v150, s[84:85] sc1
	s_add_u32 s84, s84, s62
	s_addc_u32 s85, s85, 0
	s_waitcnt vmcnt(22)
	v_pk_add_f32 v[36:37], v[36:37], v[168:169]
	v_pk_add_f32 v[38:39], v[38:39], v[170:171]
	s_waitcnt vmcnt(21)
	v_pk_add_f32 v[40:41], v[40:41], v[172:173]
	v_pk_add_f32 v[42:43], v[42:43], v[174:175]
	s_waitcnt vmcnt(20)
	v_pk_add_f32 v[44:45], v[44:45], v[176:177]
	v_pk_add_f32 v[46:47], v[46:47], v[178:179]
	s_waitcnt vmcnt(19)
	v_pk_add_f32 v[48:49], v[48:49], v[180:181]
	v_pk_add_f32 v[50:51], v[50:51], v[182:183]
	s_waitcnt vmcnt(18)
	v_pk_add_f32 v[52:53], v[52:53], v[184:185]
	v_pk_add_f32 v[54:55], v[54:55], v[186:187]
	s_waitcnt vmcnt(17)
	v_pk_add_f32 v[56:57], v[56:57], v[192:193]
	v_pk_add_f32 v[58:59], v[58:59], v[194:195]
	s_waitcnt vmcnt(16)
	v_pk_add_f32 v[60:61], v[60:61], v[196:197]
	v_pk_add_f32 v[62:63], v[62:63], v[198:199]
	s_waitcnt vmcnt(15)
	v_pk_add_f32 v[64:65], v[64:65], v[200:201]
	v_pk_add_f32 v[66:67], v[66:67], v[202:203]
	s_waitcnt vmcnt(14)
	v_pk_add_f32 v[68:69], v[68:69], v[204:205]
	v_pk_add_f32 v[70:71], v[70:71], v[206:207]
	s_waitcnt vmcnt(13)
	v_pk_add_f32 v[72:73], v[72:73], v[208:209]
	v_pk_add_f32 v[74:75], v[74:75], v[210:211]
	s_waitcnt vmcnt(12)
	v_pk_add_f32 v[76:77], v[76:77], v[212:213]
	v_pk_add_f32 v[78:79], v[78:79], v[214:215]
	s_waitcnt vmcnt(11)
	v_pk_add_f32 v[80:81], v[80:81], v[216:217]
	v_pk_add_f32 v[82:83], v[82:83], v[218:219]
	s_waitcnt vmcnt(10)
	v_pk_add_f32 v[84:85], v[84:85], v[228:229]
	v_pk_add_f32 v[86:87], v[86:87], v[230:231]
	s_waitcnt vmcnt(9)
	v_pk_add_f32 v[88:89], v[88:89], v[232:233]
	v_pk_add_f32 v[90:91], v[90:91], v[234:235]
	s_waitcnt vmcnt(8)
	v_pk_add_f32 v[92:93], v[92:93], v[236:237]
	v_pk_add_f32 v[94:95], v[94:95], v[238:239]
	s_waitcnt vmcnt(7)
	v_pk_add_f32 v[96:97], v[96:97], v[240:241]
	v_pk_add_f32 v[98:99], v[98:99], v[242:243]
	s_waitcnt vmcnt(6)
	v_pk_add_f32 v[100:101], v[100:101], v[244:245]
	v_pk_add_f32 v[102:103], v[102:103], v[246:247]
	s_waitcnt vmcnt(5)
	v_pk_add_f32 v[104:105], v[104:105], v[248:249]
	v_pk_add_f32 v[106:107], v[106:107], v[250:251]
	s_waitcnt vmcnt(4)
	v_pk_add_f32 v[108:109], v[108:109], v[252:253]
	v_pk_add_f32 v[110:111], v[110:111], v[254:255]
	s_waitcnt vmcnt(3)
	v_pk_add_f32 v[112:113], v[112:113], v[152:153]
	v_pk_add_f32 v[114:115], v[114:115], v[154:155]
	s_waitcnt vmcnt(2)
	v_pk_add_f32 v[116:117], v[116:117], v[156:157]
	v_pk_add_f32 v[118:119], v[118:119], v[158:159]
	s_waitcnt vmcnt(1)
	v_pk_add_f32 v[120:121], v[120:121], v[160:161]
	v_pk_add_f32 v[122:123], v[122:123], v[162:163]
	s_waitcnt vmcnt(0)
	v_pk_add_f32 v[124:125], v[124:125], v[164:165]
	v_pk_add_f32 v[126:127], v[126:127], v[166:167]
	s_branch .Lsk8_epi
